# all-edits variant + GEMM phases: per-block s_setprio flips deleted, one static s_setprio 1 for the trailing half (waves 4-7) per phase (timing 1)
# speedup vs baseline: 1.0164x; 1.0052x over previous
.LBB0_18:
	s_add_u32 s14, s74, 0x23400000
	s_addc_u32 s15, s75, 0
	s_lshl_b32 s8, s8, 5
	s_and_b32 s8, s8, 0x60
	s_add_i32 m0, s31, 0x18000
	v_lshl_add_u64 v[6:7], v[6:7], 0, s[26:27]
	s_lshl_b32 s37, s13, 6
	s_lshl_b32 s13, s13, 13
	s_lshl_b32 s33, s8, 7
	s_waitcnt vmcnt(2)
	s_barrier
	global_load_lds_dwordx4 v[6:7], off
	v_lshl_add_u64 v[4:5], v[4:5], 0, s[26:27]
	s_add_i32 m0, s31, 0x1a000
	s_add_i32 s38, s31, 0x8000
	s_add_i32 s39, s31, 0xa000
	global_load_lds_dwordx4 v[4:5], off
	v_lshl_add_u64 v[0:1], v[0:1], 0, s[26:27]
	s_mov_b32 m0, s38
	s_add_u32 s20, s58, 0x80080
	global_load_lds_dwordx4 v[0:1], off
	v_lshl_add_u64 v[0:1], v[2:3], 0, s[26:27]
	s_mov_b32 m0, s39
	s_addc_u32 s21, s59, 0
	global_load_lds_dwordx4 v[0:1], off
	s_add_i32 m0, s31, 0x1c000
	v_lshl_add_u64 v[0:1], s[20:21], 0, v[184:185]
	global_load_lds_dwordx4 v[0:1], off
	v_lshl_add_u64 v[0:1], s[20:21], 0, v[128:129]
	s_add_i32 m0, s31, 0x1e000
	v_and_b32_e32 v140, 15, v8
	global_load_lds_dwordx4 v[0:1], off
	v_lshrrev_b32_e32 v0, 1, v8
	v_and_b32_e32 v0, 24, v0
	v_lshlrev_b32_e32 v1, 1, v0
	v_lshlrev_b32_e32 v2, 2, v8
	v_or_b32_e32 v142, s8, v0
	v_lshlrev_b32_e32 v0, 15, v13
	v_lshl_or_b32 v1, v140, 6, v1
	v_and_b32_e32 v2, 32, v2
	v_and_b32_e32 v0, 0xffff0000, v0
	v_bitop3_b32 v3, v1, s13, v2 bitop3:0xde
	v_bitop3_b32 v141, v1, s33, v2 bitop3:0xde
	v_lshl_add_u32 v0, v12, 12, v0
	v_and_b32_e32 v1, 1, v13
	v_lshl_or_b32 v0, v1, 6, v0
	v_lshl_add_u32 v134, v14, 1, v0
	v_lshlrev_b32_e32 v0, 15, v9
	v_and_b32_e32 v0, 0xffff0000, v0
	s_waitcnt vmcnt(6)
	v_lshl_add_u32 v0, v10, 12, v0
	v_and_b32_e32 v1, 1, v9
	s_cmpk_lt_u32 s12, 0x100
	v_lshl_or_b32 v0, v1, 6, v0
	v_readlane_b32 s12, v255, 7
	s_cselect_b64 s[42:43], -1, 0
	v_mov_b32_e32 v135, v185
	v_lshl_add_u32 v136, v11, 1, v0
	v_mov_b32_e32 v137, v185
	s_mov_b32 s48, 0
	v_add_u32_e32 v143, 0, v3
	v_readlane_b32 s49, v255, 6
	s_mov_b32 s50, s12
	s_barrier
	v_readlane_b32 s13, v255, 8
	v_and_b32_e32 v246, 15, v203
	v_bfe_u32 v247, v203, 4, 2
	v_lshrrev_b32_e32 v248, 1, v246
	v_xor_b32_e32 v249, v247, v248
	v_lshlrev_b32_e32 v249, 4, v249
	v_lshrrev_b32_e32 v250, 3, v246
	v_lshlrev_b32_e32 v250, 10, v250
	v_and_b32_e32 v251, 7, v246
	v_lshl_add_u32 v250, v251, 7, v250
	v_add_u32_e32 v250, v250, v249
	v_lshrrev_b32_e32 v251, 8, v203
	v_lshl_add_u32 v143, v251, 13, v250
	v_xor_b32_e32 v240, 64, v143
	v_bfe_u32 v251, v203, 6, 2
	v_lshl_add_u32 v141, v251, 12, v250
	v_xor_b32_e32 v241, 64, v141
	v_mov_b32_e32 v134, v132
	v_mov_b32_e32 v136, v130
	v_readfirstlane_b32 s98, v203
	s_nop 3
	s_lshr_b32 s98, s98, 8
	s_cmp_lg_u32 s98, 0
	s_cbranch_scc0 .Lgp_21
	s_setprio 1
.Lgp_21:
	s_branch .LBB0_21
.LBB0_19:
	s_mov_b64 s[12:13], 0

.LBB0_28:
	s_add_u32 s8, s56, 0xfff80080
	s_addc_u32 s12, s57, -1
	s_add_i32 s20, 0, 0x10000
	s_cmp_eq_u32 s63, 28
	s_cselect_b32 s13, s47, s12
	s_cselect_b32 s12, s51, s8
	v_add_u32_e32 v138, s20, v141
	v_add_u32_e32 v238, s20, v241
	s_cselect_b32 s59, s45, s62
	s_cselect_b32 s58, s60, s61
	s_add_i32 s8, 0, 0x14000
	ds_read_b128 v[144:147], v138
	ds_read_b128 v[148:151], v238
	ds_read_b128 v[152:155], v138 offset:2048
	ds_read_b128 v[156:159], v238 offset:2048
	v_add_u32_e32 v138, s8, v141
	v_add_u32_e32 v238, s8, v241
	ds_read_b128 v[160:163], v138
	ds_read_b128 v[164:167], v238
	ds_read_b128 v[168:171], v138 offset:2048
	ds_read_b128 v[172:175], v238 offset:2048
	v_lshl_add_u64 v[138:139], s[56:57], 0, v[134:135]
	s_add_i32 m0, s31, 0xc000
	ds_read_b128 v[176:179], v143
	ds_read_b128 v[180:183], v240
	ds_read_b128 v[186:189], v143 offset:2048
	ds_read_b128 v[192:195], v240 offset:2048
	ds_read_b128 v[196:199], v143 offset:4096
	ds_read_b128 v[214:217], v240 offset:4096
	ds_read_b128 v[218:221], v143 offset:6144
	ds_read_b128 v[222:225], v240 offset:6144
	global_load_lds_dwordx4 v[138:139], off
	v_lshl_add_u64 v[138:139], s[56:57], 0, v[136:137]
	s_add_i32 m0, s31, 0xe000
	s_nop 0
	global_load_lds_dwordx4 v[138:139], off
	s_waitcnt vmcnt(8)
	s_waitcnt lgkmcnt(0)
	s_barrier
	s_waitcnt lgkmcnt(0)
	v_mfma_f32_16x16x32_bf16 v[124:127], v[144:147], v[176:179], v[124:127]
	v_mfma_f32_16x16x32_bf16 v[120:123], v[152:155], v[176:179], v[120:123]
	v_mfma_f32_16x16x32_bf16 v[108:111], v[152:155], v[186:189], v[108:111]
	v_mfma_f32_16x16x32_bf16 v[116:119], v[144:147], v[186:189], v[116:119]
	v_mfma_f32_16x16x32_bf16 v[100:103], v[144:147], v[196:199], v[100:103]
	v_mfma_f32_16x16x32_bf16 v[92:95], v[152:155], v[196:199], v[92:95]
	v_mfma_f32_16x16x32_bf16 v[76:79], v[152:155], v[218:221], v[76:79]
	v_mfma_f32_16x16x32_bf16 v[84:87], v[144:147], v[218:221], v[84:87]
	v_mfma_f32_16x16x32_bf16 v[124:127], v[148:151], v[180:183], v[124:127]
	v_mfma_f32_16x16x32_bf16 v[120:123], v[156:159], v[180:183], v[120:123]
	v_mfma_f32_16x16x32_bf16 v[108:111], v[156:159], v[192:195], v[108:111]
	v_mfma_f32_16x16x32_bf16 v[116:119], v[148:151], v[192:195], v[116:119]
	v_mfma_f32_16x16x32_bf16 v[100:103], v[148:151], v[214:217], v[100:103]
	v_mfma_f32_16x16x32_bf16 v[92:95], v[156:159], v[214:217], v[92:95]
	v_mfma_f32_16x16x32_bf16 v[76:79], v[156:159], v[222:225], v[76:79]
	v_mfma_f32_16x16x32_bf16 v[84:87], v[148:151], v[222:225], v[84:87]
	v_mfma_f32_16x16x32_bf16 v[112:115], v[160:163], v[176:179], v[112:115]
	v_mfma_f32_16x16x32_bf16 v[104:107], v[168:171], v[176:179], v[104:107]
	v_mfma_f32_16x16x32_bf16 v[88:91], v[168:171], v[186:189], v[88:91]
	v_mfma_f32_16x16x32_bf16 v[96:99], v[160:163], v[186:189], v[96:99]
	v_mfma_f32_16x16x32_bf16 v[80:83], v[160:163], v[196:199], v[80:83]
	v_mfma_f32_16x16x32_bf16 v[72:75], v[168:171], v[196:199], v[72:75]
	v_mfma_f32_16x16x32_bf16 v[64:67], v[168:171], v[218:221], v[64:67]
	v_mfma_f32_16x16x32_bf16 v[68:71], v[160:163], v[218:221], v[68:71]
	v_mfma_f32_16x16x32_bf16 v[112:115], v[164:167], v[180:183], v[112:115]
	v_mfma_f32_16x16x32_bf16 v[104:107], v[172:175], v[180:183], v[104:107]
	v_mfma_f32_16x16x32_bf16 v[88:91], v[172:175], v[192:195], v[88:91]
	v_mfma_f32_16x16x32_bf16 v[96:99], v[164:167], v[192:195], v[96:99]
	v_mfma_f32_16x16x32_bf16 v[80:83], v[164:167], v[214:217], v[80:83]
	v_mfma_f32_16x16x32_bf16 v[72:75], v[172:175], v[214:217], v[72:75]
	v_mfma_f32_16x16x32_bf16 v[64:67], v[172:175], v[222:225], v[64:67]
	v_mfma_f32_16x16x32_bf16 v[68:71], v[164:167], v[222:225], v[68:71]
	s_barrier
	s_add_i32 s20, s20, s30
	v_lshl_add_u64 v[138:139], s[58:59], 0, v[184:185]
	s_mov_b32 m0, s20
	ds_read_b128 v[176:179], v143 offset:16384
	ds_read_b128 v[180:183], v240 offset:16384
	ds_read_b128 v[186:189], v143 offset:18432
	ds_read_b128 v[192:195], v240 offset:18432
	ds_read_b128 v[196:199], v143 offset:20480
	ds_read_b128 v[214:217], v240 offset:20480
	ds_read_b128 v[218:221], v143 offset:22528
	ds_read_b128 v[222:225], v240 offset:22528
	global_load_lds_dwordx4 v[138:139], off
	s_add_i32 m0, s20, 0x2000
	s_add_u32 s20, s58, 0x80000
	v_lshl_add_u64 v[200:201], s[58:59], 0, v[128:129]
	s_addc_u32 s21, s59, 0
	s_add_i32 s8, s8, s30
	global_load_lds_dwordx4 v[200:201], off
	v_lshl_add_u64 v[226:227], s[20:21], 0, v[184:185]
	s_mov_b32 m0, s8
	v_lshl_add_u64 v[228:229], s[12:13], 0, v[130:131]
	global_load_lds_dwordx4 v[226:227], off
	v_lshl_add_u64 v[226:227], s[20:21], 0, v[128:129]
	s_add_i32 m0, s8, 0x2000
	s_nop 0
	global_load_lds_dwordx4 v[226:227], off
	v_lshl_add_u64 v[226:227], s[12:13], 0, v[132:133]
	s_mov_b32 m0, s31
	s_nop 0
	global_load_lds_dwordx4 v[226:227], off
	s_mov_b32 m0, s34
	s_nop 0
	global_load_lds_dwordx4 v[228:229], off
	s_waitcnt vmcnt(8)
	s_waitcnt lgkmcnt(0)
	s_barrier
	s_waitcnt lgkmcnt(0)
	v_mfma_f32_16x16x32_bf16 v[60:63], v[144:147], v[176:179], v[60:63]
	v_mfma_f32_16x16x32_bf16 v[56:59], v[152:155], v[176:179], v[56:59]
	v_mfma_f32_16x16x32_bf16 v[44:47], v[152:155], v[186:189], v[44:47]
	v_mfma_f32_16x16x32_bf16 v[52:55], v[144:147], v[186:189], v[52:55]
	v_mfma_f32_16x16x32_bf16 v[36:39], v[144:147], v[196:199], v[36:39]
	v_mfma_f32_16x16x32_bf16 v[28:31], v[152:155], v[196:199], v[28:31]
	v_mfma_f32_16x16x32_bf16 v[12:15], v[152:155], v[218:221], v[12:15]
	v_mfma_f32_16x16x32_bf16 v[20:23], v[144:147], v[218:221], v[20:23]
	v_mfma_f32_16x16x32_bf16 v[60:63], v[148:151], v[180:183], v[60:63]
	v_mfma_f32_16x16x32_bf16 v[56:59], v[156:159], v[180:183], v[56:59]
	v_mfma_f32_16x16x32_bf16 v[44:47], v[156:159], v[192:195], v[44:47]
	v_mfma_f32_16x16x32_bf16 v[52:55], v[148:151], v[192:195], v[52:55]
	v_mfma_f32_16x16x32_bf16 v[36:39], v[148:151], v[214:217], v[36:39]
	v_mfma_f32_16x16x32_bf16 v[28:31], v[156:159], v[214:217], v[28:31]
	v_mfma_f32_16x16x32_bf16 v[12:15], v[156:159], v[222:225], v[12:15]
	v_mfma_f32_16x16x32_bf16 v[20:23], v[148:151], v[222:225], v[20:23]
	v_mfma_f32_16x16x32_bf16 v[48:51], v[160:163], v[176:179], v[48:51]
	v_mfma_f32_16x16x32_bf16 v[40:43], v[168:171], v[176:179], v[40:43]
	v_mfma_f32_16x16x32_bf16 v[24:27], v[168:171], v[186:189], v[24:27]
	v_mfma_f32_16x16x32_bf16 v[32:35], v[160:163], v[186:189], v[32:35]
	v_mfma_f32_16x16x32_bf16 v[16:19], v[160:163], v[196:199], v[16:19]
	v_mfma_f32_16x16x32_bf16 v[8:11], v[168:171], v[196:199], v[8:11]
	v_mfma_f32_16x16x32_bf16 v[0:3], v[168:171], v[218:221], v[0:3]
	v_mfma_f32_16x16x32_bf16 v[4:7], v[160:163], v[218:221], v[4:7]
	v_mfma_f32_16x16x32_bf16 v[48:51], v[164:167], v[180:183], v[48:51]
	v_mfma_f32_16x16x32_bf16 v[40:43], v[172:175], v[180:183], v[40:43]
	v_mfma_f32_16x16x32_bf16 v[24:27], v[172:175], v[192:195], v[24:27]
	v_mfma_f32_16x16x32_bf16 v[32:35], v[164:167], v[192:195], v[32:35]
	v_mfma_f32_16x16x32_bf16 v[16:19], v[164:167], v[214:217], v[16:19]
	v_mfma_f32_16x16x32_bf16 v[8:11], v[172:175], v[214:217], v[8:11]
	v_mfma_f32_16x16x32_bf16 v[0:3], v[172:175], v[222:225], v[0:3]
	v_mfma_f32_16x16x32_bf16 v[4:7], v[164:167], v[222:225], v[4:7]
	s_barrier
	s_add_i32 s8, 0, 0x18000
	s_add_i32 s20, 0, 0x1c000
	v_add_u32_e32 v156, s8, v141
	v_add_u32_e32 v238, s8, v241
	v_add_u32_e32 v172, s20, v141
	v_add_u32_e32 v239, s20, v241
	ds_read_b128 v[144:147], v156
	ds_read_b128 v[148:151], v238
	ds_read_b128 v[152:155], v156 offset:2048
	ds_read_b128 v[156:159], v238 offset:2048
	ds_read_b128 v[160:163], v172
	ds_read_b128 v[164:167], v239
	ds_read_b128 v[168:171], v172 offset:2048
	ds_read_b128 v[172:175], v239 offset:2048
	s_add_u32 s12, s12, 0x80000
	s_addc_u32 s13, s13, 0
	s_mov_b32 m0, s35
	v_lshl_add_u64 v[230:231], s[12:13], 0, v[132:133]
	ds_read_b128 v[176:179], v143 offset:32768
	ds_read_b128 v[180:183], v240 offset:32768
	ds_read_b128 v[186:189], v143 offset:34816
	ds_read_b128 v[192:195], v240 offset:34816
	ds_read_b128 v[196:199], v143 offset:36864
	ds_read_b128 v[214:217], v240 offset:36864
	ds_read_b128 v[218:221], v143 offset:38912
	ds_read_b128 v[222:225], v240 offset:38912
	global_load_lds_dwordx4 v[230:231], off
	v_lshl_add_u64 v[230:231], s[12:13], 0, v[130:131]
	s_mov_b32 m0, s36
	s_nop 0
	global_load_lds_dwordx4 v[230:231], off
	s_waitcnt vmcnt(8)
	s_waitcnt lgkmcnt(0)
	s_barrier
	s_waitcnt lgkmcnt(0)
	v_mfma_f32_16x16x32_bf16 v[124:127], v[144:147], v[176:179], v[124:127]
	v_mfma_f32_16x16x32_bf16 v[120:123], v[152:155], v[176:179], v[120:123]
	v_mfma_f32_16x16x32_bf16 v[108:111], v[152:155], v[186:189], v[108:111]
	v_mfma_f32_16x16x32_bf16 v[116:119], v[144:147], v[186:189], v[116:119]
	v_mfma_f32_16x16x32_bf16 v[100:103], v[144:147], v[196:199], v[100:103]
	v_mfma_f32_16x16x32_bf16 v[92:95], v[152:155], v[196:199], v[92:95]
	v_mfma_f32_16x16x32_bf16 v[76:79], v[152:155], v[218:221], v[76:79]
	v_mfma_f32_16x16x32_bf16 v[84:87], v[144:147], v[218:221], v[84:87]
	v_mfma_f32_16x16x32_bf16 v[124:127], v[148:151], v[180:183], v[124:127]
	v_mfma_f32_16x16x32_bf16 v[120:123], v[156:159], v[180:183], v[120:123]
	v_mfma_f32_16x16x32_bf16 v[108:111], v[156:159], v[192:195], v[108:111]
	v_mfma_f32_16x16x32_bf16 v[116:119], v[148:151], v[192:195], v[116:119]
	v_mfma_f32_16x16x32_bf16 v[100:103], v[148:151], v[214:217], v[100:103]
	v_mfma_f32_16x16x32_bf16 v[92:95], v[156:159], v[214:217], v[92:95]
	v_mfma_f32_16x16x32_bf16 v[76:79], v[156:159], v[222:225], v[76:79]
	v_mfma_f32_16x16x32_bf16 v[84:87], v[148:151], v[222:225], v[84:87]
	v_mfma_f32_16x16x32_bf16 v[112:115], v[160:163], v[176:179], v[112:115]
	v_mfma_f32_16x16x32_bf16 v[104:107], v[168:171], v[176:179], v[104:107]
	v_mfma_f32_16x16x32_bf16 v[88:91], v[168:171], v[186:189], v[88:91]
	v_mfma_f32_16x16x32_bf16 v[96:99], v[160:163], v[186:189], v[96:99]
	v_mfma_f32_16x16x32_bf16 v[80:83], v[160:163], v[196:199], v[80:83]
	v_mfma_f32_16x16x32_bf16 v[72:75], v[168:171], v[196:199], v[72:75]
	v_mfma_f32_16x16x32_bf16 v[64:67], v[168:171], v[218:221], v[64:67]
	v_mfma_f32_16x16x32_bf16 v[68:71], v[160:163], v[218:221], v[68:71]
	v_mfma_f32_16x16x32_bf16 v[112:115], v[164:167], v[180:183], v[112:115]
	v_mfma_f32_16x16x32_bf16 v[104:107], v[172:175], v[180:183], v[104:107]
	v_mfma_f32_16x16x32_bf16 v[88:91], v[172:175], v[192:195], v[88:91]
	v_mfma_f32_16x16x32_bf16 v[96:99], v[164:167], v[192:195], v[96:99]
	v_mfma_f32_16x16x32_bf16 v[80:83], v[164:167], v[214:217], v[80:83]
	v_mfma_f32_16x16x32_bf16 v[72:75], v[172:175], v[214:217], v[72:75]
	v_mfma_f32_16x16x32_bf16 v[64:67], v[172:175], v[222:225], v[64:67]
	v_mfma_f32_16x16x32_bf16 v[68:71], v[164:167], v[222:225], v[68:71]
	s_barrier
	s_add_i32 s8, s8, s30
	v_lshl_add_u64 v[138:139], v[138:139], 0, s[26:27]
	s_mov_b32 m0, s8
	ds_read_b128 v[176:179], v143 offset:49152
	ds_read_b128 v[180:183], v240 offset:49152
	ds_read_b128 v[186:189], v143 offset:51200
	ds_read_b128 v[192:195], v240 offset:51200
	ds_read_b128 v[196:199], v143 offset:53248
	ds_read_b128 v[214:217], v240 offset:53248
	ds_read_b128 v[218:221], v143 offset:55296
	ds_read_b128 v[222:225], v240 offset:55296
	global_load_lds_dwordx4 v[138:139], off
	s_add_i32 m0, s8, 0x2000
	s_add_u32 s12, s58, 0x80080
	v_lshl_add_u64 v[138:139], v[200:201], 0, s[26:27]
	s_addc_u32 s13, s59, 0
	s_add_i32 s8, s20, s30
	global_load_lds_dwordx4 v[138:139], off
	v_lshl_add_u64 v[138:139], s[12:13], 0, v[184:185]
	s_mov_b32 m0, s8
	s_nop 0
	global_load_lds_dwordx4 v[138:139], off
	v_lshl_add_u64 v[138:139], s[12:13], 0, v[128:129]
	s_add_i32 m0, s8, 0x2000
	s_nop 0
	global_load_lds_dwordx4 v[138:139], off
	v_lshl_add_u64 v[138:139], v[226:227], 0, s[26:27]
	s_mov_b32 m0, s38
	s_nop 0
	global_load_lds_dwordx4 v[138:139], off
	v_lshl_add_u64 v[138:139], v[228:229], 0, s[26:27]
	s_mov_b32 m0, s39
	s_nop 0
	global_load_lds_dwordx4 v[138:139], off
	s_waitcnt vmcnt(8)
	s_waitcnt lgkmcnt(0)
	s_barrier
	s_waitcnt lgkmcnt(0)
	v_mfma_f32_16x16x32_bf16 v[60:63], v[144:147], v[176:179], v[60:63]
	v_mfma_f32_16x16x32_bf16 v[56:59], v[152:155], v[176:179], v[56:59]
	v_mfma_f32_16x16x32_bf16 v[44:47], v[152:155], v[186:189], v[44:47]
	v_mfma_f32_16x16x32_bf16 v[52:55], v[144:147], v[186:189], v[52:55]
	v_mfma_f32_16x16x32_bf16 v[36:39], v[144:147], v[196:199], v[36:39]
	v_mfma_f32_16x16x32_bf16 v[28:31], v[152:155], v[196:199], v[28:31]
	v_mfma_f32_16x16x32_bf16 v[12:15], v[152:155], v[218:221], v[12:15]
	v_mfma_f32_16x16x32_bf16 v[20:23], v[144:147], v[218:221], v[20:23]
	v_mfma_f32_16x16x32_bf16 v[60:63], v[148:151], v[180:183], v[60:63]
	v_mfma_f32_16x16x32_bf16 v[56:59], v[156:159], v[180:183], v[56:59]
	v_mfma_f32_16x16x32_bf16 v[44:47], v[156:159], v[192:195], v[44:47]
	v_mfma_f32_16x16x32_bf16 v[52:55], v[148:151], v[192:195], v[52:55]
	v_mfma_f32_16x16x32_bf16 v[36:39], v[148:151], v[214:217], v[36:39]
	v_mfma_f32_16x16x32_bf16 v[28:31], v[156:159], v[214:217], v[28:31]
	v_mfma_f32_16x16x32_bf16 v[12:15], v[156:159], v[222:225], v[12:15]
	v_mfma_f32_16x16x32_bf16 v[20:23], v[148:151], v[222:225], v[20:23]
	v_mfma_f32_16x16x32_bf16 v[48:51], v[160:163], v[176:179], v[48:51]
	v_mfma_f32_16x16x32_bf16 v[40:43], v[168:171], v[176:179], v[40:43]
	v_mfma_f32_16x16x32_bf16 v[24:27], v[168:171], v[186:189], v[24:27]
	v_mfma_f32_16x16x32_bf16 v[32:35], v[160:163], v[186:189], v[32:35]
	v_mfma_f32_16x16x32_bf16 v[16:19], v[160:163], v[196:199], v[16:19]
	v_mfma_f32_16x16x32_bf16 v[8:11], v[168:171], v[196:199], v[8:11]
	v_mfma_f32_16x16x32_bf16 v[0:3], v[168:171], v[218:221], v[0:3]
	v_mfma_f32_16x16x32_bf16 v[4:7], v[160:163], v[218:221], v[4:7]
	v_mfma_f32_16x16x32_bf16 v[48:51], v[164:167], v[180:183], v[48:51]
	v_mfma_f32_16x16x32_bf16 v[40:43], v[172:175], v[180:183], v[40:43]
	v_mfma_f32_16x16x32_bf16 v[24:27], v[172:175], v[192:195], v[24:27]
	v_mfma_f32_16x16x32_bf16 v[32:35], v[164:167], v[192:195], v[32:35]
	v_mfma_f32_16x16x32_bf16 v[16:19], v[164:167], v[214:217], v[16:19]
	v_mfma_f32_16x16x32_bf16 v[8:11], v[172:175], v[214:217], v[8:11]
	v_mfma_f32_16x16x32_bf16 v[0:3], v[172:175], v[222:225], v[0:3]
	v_mfma_f32_16x16x32_bf16 v[4:7], v[164:167], v[222:225], v[4:7]
	s_barrier
	s_add_i32 s63, s63, 2
	s_add_u32 s56, s56, 0x100
	s_addc_u32 s57, s57, 0
	s_add_u32 s61, s61, 0x100
	s_addc_u32 s62, s62, 0
	s_cmp_gt_u32 s63, 29
	s_cbranch_scc0 .LBB0_28
	s_and_b64 vcc, exec, s[42:43]
	s_cbranch_vccz .LBB0_31
	s_barrier

.LBB0_36:
	s_setprio 0
	s_mov_b64 s[6:7], 0

.LBB0_176:
	s_add_u32 s56, s74, 0x23400000
	s_addc_u32 s57, s75, 0
	s_add_u32 s58, s74, 0xac00000
	s_addc_u32 s59, s75, 0
	s_add_u32 s60, s74, 0xad80000
	s_addc_u32 s61, s75, 0
	s_and_b32 s71, s8, 3
	s_add_i32 m0, s30, 0x18000
	v_lshl_add_u64 v[6:7], v[6:7], 0, s[26:27]
	s_lshl_b32 s96, s7, 6
	s_lshl_b32 s7, s7, 13
	s_lshl_b32 s12, s71, 12
	s_waitcnt vmcnt(2)
	s_barrier
	global_load_lds_dwordx4 v[6:7], off
	v_lshl_add_u64 v[4:5], v[4:5], 0, s[26:27]
	s_add_i32 m0, s30, 0x1a000
	s_add_i32 s34, s30, 0x8000
	s_add_i32 s35, s30, 0xa000
	global_load_lds_dwordx4 v[4:5], off
	v_lshl_add_u64 v[0:1], v[0:1], 0, s[26:27]
	s_mov_b32 m0, s34
	s_add_u32 s8, s44, 0x80080
	global_load_lds_dwordx4 v[0:1], off
	v_lshl_add_u64 v[0:1], v[2:3], 0, s[26:27]
	s_mov_b32 m0, s35
	s_addc_u32 s9, s45, 0
	global_load_lds_dwordx4 v[0:1], off
	s_add_i32 m0, s30, 0x1c000
	v_lshl_add_u64 v[0:1], s[8:9], 0, v[184:185]
	global_load_lds_dwordx4 v[0:1], off
	v_lshl_add_u64 v[0:1], s[8:9], 0, v[128:129]
	s_add_i32 m0, s30, 0x1e000
	v_and_b32_e32 v146, 15, v8
	global_load_lds_dwordx4 v[0:1], off
	v_bfe_u32 v0, v8, 4, 2
	v_lshlrev_b32_e32 v1, 3, v0
	v_lshlrev_b32_e32 v2, 4, v0
	v_cmp_eq_u32_e64 s[40:41], 0, v0
	v_lshlrev_b32_e32 v0, 15, v13
	v_and_b32_e32 v0, 0xffff0000, v0
	v_lshl_or_b32 v148, s71, 5, v1
	v_lshl_add_u32 v0, v12, 12, v0
	v_and_b32_e32 v1, 1, v13
	v_lshl_or_b32 v0, v1, 6, v0
	v_lshl_add_u32 v134, v14, 1, v0
	v_lshlrev_b32_e32 v0, 15, v9
	v_lshlrev_b32_e32 v3, 2, v8
	v_and_b32_e32 v0, 0xffff0000, v0
	v_lshl_or_b32 v2, v146, 6, v2
	v_and_b32_e32 v3, 32, v3
	s_waitcnt vmcnt(6)
	v_lshl_add_u32 v0, v10, 12, v0
	v_and_b32_e32 v1, 1, v9
	v_bitop3_b32 v4, v2, s7, v3 bitop3:0xde
	s_cmpk_lt_u32 s6, 0x100
	v_lshl_or_b32 v0, v1, 6, v0
	v_readlane_b32 s6, v255, 40
	v_bitop3_b32 v147, v2, s12, v3 bitop3:0xde
	s_cselect_b64 s[62:63], -1, 0
	s_mov_b32 s36, 0
	v_mov_b32_e32 v135, v185
	v_lshl_add_u32 v136, v11, 1, v0
	v_mov_b32_e32 v137, v185
	v_add_u32_e32 v149, 0, v4
	v_readlane_b32 s9, v255, 26
	s_mov_b32 s16, s6
	s_barrier
	v_readlane_b32 s7, v255, 41
	v_and_b32_e32 v246, 15, v203
	v_bfe_u32 v247, v203, 4, 2
	v_lshrrev_b32_e32 v248, 1, v246
	v_xor_b32_e32 v249, v247, v248
	v_lshlrev_b32_e32 v249, 4, v249
	v_lshrrev_b32_e32 v250, 3, v246
	v_lshlrev_b32_e32 v250, 10, v250
	v_and_b32_e32 v251, 7, v246
	v_lshl_add_u32 v250, v251, 7, v250
	v_add_u32_e32 v250, v250, v249
	v_lshrrev_b32_e32 v251, 8, v203
	v_lshl_add_u32 v149, v251, 13, v250
	v_xor_b32_e32 v240, 64, v149
	v_bfe_u32 v251, v203, 6, 2
	v_lshl_add_u32 v147, v251, 12, v250
	v_xor_b32_e32 v241, 64, v147
	v_mov_b32_e32 v134, v132
	v_mov_b32_e32 v136, v130
	v_readfirstlane_b32 s98, v203
	s_nop 3
	s_lshr_b32 s98, s98, 8
	s_cmp_lg_u32 s98, 0
	s_cbranch_scc0 .Lgp_179
	s_setprio 1
.Lgp_179:
	s_branch .LBB0_179
.LBB0_177:
	s_mov_b64 s[12:13], 0

.LBB0_182:
	s_add_u32 s8, s14, 0xfff80080
	s_addc_u32 s12, s15, -1
	s_add_i32 s20, 0, 0x10000
	s_cmp_eq_u32 s51, 28
	s_cselect_b32 s13, s37, s12
	s_cselect_b32 s12, s46, s8
	s_cselect_b32 s45, s47, s50
	s_cselect_b32 s44, s48, s49
	s_add_i32 s8, 0, 0x14000
	v_add_u32_e32 v154, s20, v147
	v_add_u32_e32 v238, s20, v241
	v_add_u32_e32 v170, s8, v147
	v_add_u32_e32 v239, s8, v241
	ds_read_b128 v[138:141], v154
	ds_read_b128 v[142:145], v238
	ds_read_b128 v[150:153], v154 offset:2048
	ds_read_b128 v[154:157], v238 offset:2048
	ds_read_b128 v[158:161], v170
	ds_read_b128 v[162:165], v239
	ds_read_b128 v[166:169], v170 offset:2048
	ds_read_b128 v[170:173], v239 offset:2048
	v_lshl_add_u64 v[182:183], s[14:15], 0, v[134:135]
	s_add_i32 m0, s30, 0xc000
	ds_read_b128 v[174:177], v149
	ds_read_b128 v[178:181], v240
	ds_read_b128 v[192:195], v149 offset:2048
	ds_read_b128 v[196:199], v240 offset:2048
	ds_read_b128 v[214:217], v149 offset:4096
	ds_read_b128 v[218:221], v240 offset:4096
	ds_read_b128 v[222:225], v149 offset:6144
	ds_read_b128 v[226:229], v240 offset:6144
	global_load_lds_dwordx4 v[182:183], off
	v_lshl_add_u64 v[182:183], s[14:15], 0, v[136:137]
	s_add_i32 m0, s30, 0xe000
	s_nop 0
	global_load_lds_dwordx4 v[182:183], off
	s_waitcnt vmcnt(8)
	s_waitcnt lgkmcnt(0)
	s_barrier
	s_waitcnt lgkmcnt(0)
	v_mfma_f32_16x16x32_bf16 v[124:127], v[138:141], v[174:177], v[124:127]
	v_mfma_f32_16x16x32_bf16 v[120:123], v[150:153], v[174:177], v[120:123]
	v_mfma_f32_16x16x32_bf16 v[104:107], v[150:153], v[192:195], v[104:107]
	v_mfma_f32_16x16x32_bf16 v[108:111], v[138:141], v[192:195], v[108:111]
	v_mfma_f32_16x16x32_bf16 v[92:95], v[138:141], v[214:217], v[92:95]
	v_mfma_f32_16x16x32_bf16 v[88:91], v[150:153], v[214:217], v[88:91]
	v_mfma_f32_16x16x32_bf16 v[72:75], v[150:153], v[222:225], v[72:75]
	v_mfma_f32_16x16x32_bf16 v[76:79], v[138:141], v[222:225], v[76:79]
	v_mfma_f32_16x16x32_bf16 v[124:127], v[142:145], v[178:181], v[124:127]
	v_mfma_f32_16x16x32_bf16 v[120:123], v[154:157], v[178:181], v[120:123]
	v_mfma_f32_16x16x32_bf16 v[104:107], v[154:157], v[196:199], v[104:107]
	v_mfma_f32_16x16x32_bf16 v[108:111], v[142:145], v[196:199], v[108:111]
	v_mfma_f32_16x16x32_bf16 v[92:95], v[142:145], v[218:221], v[92:95]
	v_mfma_f32_16x16x32_bf16 v[88:91], v[154:157], v[218:221], v[88:91]
	v_mfma_f32_16x16x32_bf16 v[72:75], v[154:157], v[226:229], v[72:75]
	v_mfma_f32_16x16x32_bf16 v[76:79], v[142:145], v[226:229], v[76:79]
	v_mfma_f32_16x16x32_bf16 v[116:119], v[158:161], v[174:177], v[116:119]
	v_mfma_f32_16x16x32_bf16 v[112:115], v[166:169], v[174:177], v[112:115]
	v_mfma_f32_16x16x32_bf16 v[96:99], v[166:169], v[192:195], v[96:99]
	v_mfma_f32_16x16x32_bf16 v[100:103], v[158:161], v[192:195], v[100:103]
	v_mfma_f32_16x16x32_bf16 v[84:87], v[158:161], v[214:217], v[84:87]
	v_mfma_f32_16x16x32_bf16 v[80:83], v[166:169], v[214:217], v[80:83]
	v_mfma_f32_16x16x32_bf16 v[64:67], v[166:169], v[222:225], v[64:67]
	v_mfma_f32_16x16x32_bf16 v[68:71], v[158:161], v[222:225], v[68:71]
	v_mfma_f32_16x16x32_bf16 v[116:119], v[162:165], v[178:181], v[116:119]
	v_mfma_f32_16x16x32_bf16 v[112:115], v[170:173], v[178:181], v[112:115]
	v_mfma_f32_16x16x32_bf16 v[96:99], v[170:173], v[196:199], v[96:99]
	v_mfma_f32_16x16x32_bf16 v[100:103], v[162:165], v[196:199], v[100:103]
	v_mfma_f32_16x16x32_bf16 v[84:87], v[162:165], v[218:221], v[84:87]
	v_mfma_f32_16x16x32_bf16 v[80:83], v[170:173], v[218:221], v[80:83]
	v_mfma_f32_16x16x32_bf16 v[64:67], v[170:173], v[226:229], v[64:67]
	v_mfma_f32_16x16x32_bf16 v[68:71], v[162:165], v[226:229], v[68:71]
	s_barrier
	s_add_i32 s20, s20, s25
	v_lshl_add_u64 v[182:183], s[44:45], 0, v[184:185]
	s_mov_b32 m0, s20
	ds_read_b128 v[174:177], v149 offset:16384
	ds_read_b128 v[178:181], v240 offset:16384
	ds_read_b128 v[192:195], v149 offset:18432
	ds_read_b128 v[196:199], v240 offset:18432
	ds_read_b128 v[214:217], v149 offset:20480
	ds_read_b128 v[218:221], v240 offset:20480
	ds_read_b128 v[222:225], v149 offset:22528
	ds_read_b128 v[226:229], v240 offset:22528
	global_load_lds_dwordx4 v[182:183], off
	s_add_i32 m0, s20, 0x2000
	s_add_u32 s20, s44, 0x80000
	v_lshl_add_u64 v[186:187], s[44:45], 0, v[128:129]
	s_addc_u32 s21, s45, 0
	s_add_i32 s8, s8, s25
	global_load_lds_dwordx4 v[186:187], off
	v_lshl_add_u64 v[188:189], s[20:21], 0, v[184:185]
	s_mov_b32 m0, s8
	v_lshl_add_u64 v[200:201], s[12:13], 0, v[130:131]
	global_load_lds_dwordx4 v[188:189], off
	v_lshl_add_u64 v[188:189], s[20:21], 0, v[128:129]
	s_add_i32 m0, s8, 0x2000
	s_nop 0
	global_load_lds_dwordx4 v[188:189], off
	v_lshl_add_u64 v[188:189], s[12:13], 0, v[132:133]
	s_mov_b32 m0, s30
	s_nop 0
	global_load_lds_dwordx4 v[188:189], off
	s_mov_b32 m0, s31
	s_nop 0
	global_load_lds_dwordx4 v[200:201], off
	s_waitcnt vmcnt(8)
	s_waitcnt lgkmcnt(0)
	s_barrier
	s_waitcnt lgkmcnt(0)
	v_mfma_f32_16x16x32_bf16 v[60:63], v[138:141], v[174:177], v[60:63]
	v_mfma_f32_16x16x32_bf16 v[56:59], v[150:153], v[174:177], v[56:59]
	v_mfma_f32_16x16x32_bf16 v[40:43], v[150:153], v[192:195], v[40:43]
	v_mfma_f32_16x16x32_bf16 v[44:47], v[138:141], v[192:195], v[44:47]
	v_mfma_f32_16x16x32_bf16 v[28:31], v[138:141], v[214:217], v[28:31]
	v_mfma_f32_16x16x32_bf16 v[24:27], v[150:153], v[214:217], v[24:27]
	v_mfma_f32_16x16x32_bf16 v[8:11], v[150:153], v[222:225], v[8:11]
	v_mfma_f32_16x16x32_bf16 v[12:15], v[138:141], v[222:225], v[12:15]
	v_mfma_f32_16x16x32_bf16 v[60:63], v[142:145], v[178:181], v[60:63]
	v_mfma_f32_16x16x32_bf16 v[56:59], v[154:157], v[178:181], v[56:59]
	v_mfma_f32_16x16x32_bf16 v[40:43], v[154:157], v[196:199], v[40:43]
	v_mfma_f32_16x16x32_bf16 v[44:47], v[142:145], v[196:199], v[44:47]
	v_mfma_f32_16x16x32_bf16 v[28:31], v[142:145], v[218:221], v[28:31]
	v_mfma_f32_16x16x32_bf16 v[24:27], v[154:157], v[218:221], v[24:27]
	v_mfma_f32_16x16x32_bf16 v[8:11], v[154:157], v[226:229], v[8:11]
	v_mfma_f32_16x16x32_bf16 v[12:15], v[142:145], v[226:229], v[12:15]
	v_mfma_f32_16x16x32_bf16 v[52:55], v[158:161], v[174:177], v[52:55]
	v_mfma_f32_16x16x32_bf16 v[48:51], v[166:169], v[174:177], v[48:51]
	v_mfma_f32_16x16x32_bf16 v[32:35], v[166:169], v[192:195], v[32:35]
	v_mfma_f32_16x16x32_bf16 v[36:39], v[158:161], v[192:195], v[36:39]
	v_mfma_f32_16x16x32_bf16 v[20:23], v[158:161], v[214:217], v[20:23]
	v_mfma_f32_16x16x32_bf16 v[16:19], v[166:169], v[214:217], v[16:19]
	v_mfma_f32_16x16x32_bf16 v[0:3], v[166:169], v[222:225], v[0:3]
	v_mfma_f32_16x16x32_bf16 v[4:7], v[158:161], v[222:225], v[4:7]
	v_mfma_f32_16x16x32_bf16 v[52:55], v[162:165], v[178:181], v[52:55]
	v_mfma_f32_16x16x32_bf16 v[48:51], v[170:173], v[178:181], v[48:51]
	v_mfma_f32_16x16x32_bf16 v[32:35], v[170:173], v[196:199], v[32:35]
	v_mfma_f32_16x16x32_bf16 v[36:39], v[162:165], v[196:199], v[36:39]
	v_mfma_f32_16x16x32_bf16 v[20:23], v[162:165], v[218:221], v[20:23]
	v_mfma_f32_16x16x32_bf16 v[16:19], v[170:173], v[218:221], v[16:19]
	v_mfma_f32_16x16x32_bf16 v[0:3], v[170:173], v[226:229], v[0:3]
	v_mfma_f32_16x16x32_bf16 v[4:7], v[162:165], v[226:229], v[4:7]
	s_barrier
	s_add_i32 s8, 0, 0x18000
	s_add_i32 s20, 0, 0x1c000
	v_add_u32_e32 v154, s8, v147
	v_add_u32_e32 v238, s8, v241
	v_add_u32_e32 v170, s20, v147
	v_add_u32_e32 v239, s20, v241
	ds_read_b128 v[138:141], v154
	ds_read_b128 v[142:145], v238
	ds_read_b128 v[150:153], v154 offset:2048
	ds_read_b128 v[154:157], v238 offset:2048
	ds_read_b128 v[158:161], v170
	ds_read_b128 v[162:165], v239
	ds_read_b128 v[166:169], v170 offset:2048
	ds_read_b128 v[170:173], v239 offset:2048
	s_add_u32 s12, s12, 0x80000
	s_addc_u32 s13, s13, 0
	s_mov_b32 m0, s38
	v_lshl_add_u64 v[230:231], s[12:13], 0, v[132:133]
	ds_read_b128 v[174:177], v149 offset:32768
	ds_read_b128 v[178:181], v240 offset:32768
	ds_read_b128 v[192:195], v149 offset:34816
	ds_read_b128 v[196:199], v240 offset:34816
	ds_read_b128 v[214:217], v149 offset:36864
	ds_read_b128 v[218:221], v240 offset:36864
	ds_read_b128 v[222:225], v149 offset:38912
	ds_read_b128 v[226:229], v240 offset:38912
	global_load_lds_dwordx4 v[230:231], off
	v_lshl_add_u64 v[230:231], s[12:13], 0, v[130:131]
	s_mov_b32 m0, s39
	s_nop 0
	global_load_lds_dwordx4 v[230:231], off
	s_waitcnt vmcnt(8)
	s_waitcnt lgkmcnt(0)
	s_barrier
	s_waitcnt lgkmcnt(0)
	v_mfma_f32_16x16x32_bf16 v[124:127], v[138:141], v[174:177], v[124:127]
	v_mfma_f32_16x16x32_bf16 v[120:123], v[150:153], v[174:177], v[120:123]
	v_mfma_f32_16x16x32_bf16 v[104:107], v[150:153], v[192:195], v[104:107]
	v_mfma_f32_16x16x32_bf16 v[108:111], v[138:141], v[192:195], v[108:111]
	v_mfma_f32_16x16x32_bf16 v[92:95], v[138:141], v[214:217], v[92:95]
	v_mfma_f32_16x16x32_bf16 v[88:91], v[150:153], v[214:217], v[88:91]
	v_mfma_f32_16x16x32_bf16 v[72:75], v[150:153], v[222:225], v[72:75]
	v_mfma_f32_16x16x32_bf16 v[76:79], v[138:141], v[222:225], v[76:79]
	v_mfma_f32_16x16x32_bf16 v[124:127], v[142:145], v[178:181], v[124:127]
	v_mfma_f32_16x16x32_bf16 v[120:123], v[154:157], v[178:181], v[120:123]
	v_mfma_f32_16x16x32_bf16 v[104:107], v[154:157], v[196:199], v[104:107]
	v_mfma_f32_16x16x32_bf16 v[108:111], v[142:145], v[196:199], v[108:111]
	v_mfma_f32_16x16x32_bf16 v[92:95], v[142:145], v[218:221], v[92:95]
	v_mfma_f32_16x16x32_bf16 v[88:91], v[154:157], v[218:221], v[88:91]
	v_mfma_f32_16x16x32_bf16 v[72:75], v[154:157], v[226:229], v[72:75]
	v_mfma_f32_16x16x32_bf16 v[76:79], v[142:145], v[226:229], v[76:79]
	v_mfma_f32_16x16x32_bf16 v[116:119], v[158:161], v[174:177], v[116:119]
	v_mfma_f32_16x16x32_bf16 v[112:115], v[166:169], v[174:177], v[112:115]
	v_mfma_f32_16x16x32_bf16 v[96:99], v[166:169], v[192:195], v[96:99]
	v_mfma_f32_16x16x32_bf16 v[100:103], v[158:161], v[192:195], v[100:103]
	v_mfma_f32_16x16x32_bf16 v[84:87], v[158:161], v[214:217], v[84:87]
	v_mfma_f32_16x16x32_bf16 v[80:83], v[166:169], v[214:217], v[80:83]
	v_mfma_f32_16x16x32_bf16 v[64:67], v[166:169], v[222:225], v[64:67]
	v_mfma_f32_16x16x32_bf16 v[68:71], v[158:161], v[222:225], v[68:71]
	v_mfma_f32_16x16x32_bf16 v[116:119], v[162:165], v[178:181], v[116:119]
	v_mfma_f32_16x16x32_bf16 v[112:115], v[170:173], v[178:181], v[112:115]
	v_mfma_f32_16x16x32_bf16 v[96:99], v[170:173], v[196:199], v[96:99]
	v_mfma_f32_16x16x32_bf16 v[100:103], v[162:165], v[196:199], v[100:103]
	v_mfma_f32_16x16x32_bf16 v[84:87], v[162:165], v[218:221], v[84:87]
	v_mfma_f32_16x16x32_bf16 v[80:83], v[170:173], v[218:221], v[80:83]
	v_mfma_f32_16x16x32_bf16 v[64:67], v[170:173], v[226:229], v[64:67]
	v_mfma_f32_16x16x32_bf16 v[68:71], v[162:165], v[226:229], v[68:71]
	s_barrier
	s_add_i32 s8, s8, s25
	v_lshl_add_u64 v[182:183], v[182:183], 0, s[26:27]
	s_mov_b32 m0, s8
	ds_read_b128 v[174:177], v149 offset:49152
	ds_read_b128 v[178:181], v240 offset:49152
	ds_read_b128 v[192:195], v149 offset:51200
	ds_read_b128 v[196:199], v240 offset:51200
	ds_read_b128 v[214:217], v149 offset:53248
	ds_read_b128 v[218:221], v240 offset:53248
	ds_read_b128 v[222:225], v149 offset:55296
	ds_read_b128 v[226:229], v240 offset:55296
	global_load_lds_dwordx4 v[182:183], off
	s_add_i32 m0, s8, 0x2000
	s_add_u32 s12, s44, 0x80080
	v_lshl_add_u64 v[182:183], v[186:187], 0, s[26:27]
	s_addc_u32 s13, s45, 0
	s_add_i32 s8, s20, s25
	global_load_lds_dwordx4 v[182:183], off
	v_lshl_add_u64 v[182:183], s[12:13], 0, v[184:185]
	s_mov_b32 m0, s8
	s_nop 0
	global_load_lds_dwordx4 v[182:183], off
	v_lshl_add_u64 v[182:183], s[12:13], 0, v[128:129]
	s_add_i32 m0, s8, 0x2000
	s_nop 0
	global_load_lds_dwordx4 v[182:183], off
	v_lshl_add_u64 v[182:183], v[188:189], 0, s[26:27]
	s_mov_b32 m0, s34
	s_nop 0
	global_load_lds_dwordx4 v[182:183], off
	v_lshl_add_u64 v[182:183], v[200:201], 0, s[26:27]
	s_mov_b32 m0, s35
	s_nop 0
	global_load_lds_dwordx4 v[182:183], off
	s_waitcnt vmcnt(8)
	s_waitcnt lgkmcnt(0)
	s_barrier
	s_waitcnt lgkmcnt(0)
	v_mfma_f32_16x16x32_bf16 v[60:63], v[138:141], v[174:177], v[60:63]
	v_mfma_f32_16x16x32_bf16 v[56:59], v[150:153], v[174:177], v[56:59]
	v_mfma_f32_16x16x32_bf16 v[40:43], v[150:153], v[192:195], v[40:43]
	v_mfma_f32_16x16x32_bf16 v[44:47], v[138:141], v[192:195], v[44:47]
	v_mfma_f32_16x16x32_bf16 v[28:31], v[138:141], v[214:217], v[28:31]
	v_mfma_f32_16x16x32_bf16 v[24:27], v[150:153], v[214:217], v[24:27]
	v_mfma_f32_16x16x32_bf16 v[8:11], v[150:153], v[222:225], v[8:11]
	v_mfma_f32_16x16x32_bf16 v[12:15], v[138:141], v[222:225], v[12:15]
	v_mfma_f32_16x16x32_bf16 v[60:63], v[142:145], v[178:181], v[60:63]
	v_mfma_f32_16x16x32_bf16 v[56:59], v[154:157], v[178:181], v[56:59]
	v_mfma_f32_16x16x32_bf16 v[40:43], v[154:157], v[196:199], v[40:43]
	v_mfma_f32_16x16x32_bf16 v[44:47], v[142:145], v[196:199], v[44:47]
	v_mfma_f32_16x16x32_bf16 v[28:31], v[142:145], v[218:221], v[28:31]
	v_mfma_f32_16x16x32_bf16 v[24:27], v[154:157], v[218:221], v[24:27]
	v_mfma_f32_16x16x32_bf16 v[8:11], v[154:157], v[226:229], v[8:11]
	v_mfma_f32_16x16x32_bf16 v[12:15], v[142:145], v[226:229], v[12:15]
	v_mfma_f32_16x16x32_bf16 v[52:55], v[158:161], v[174:177], v[52:55]
	v_mfma_f32_16x16x32_bf16 v[48:51], v[166:169], v[174:177], v[48:51]
	v_mfma_f32_16x16x32_bf16 v[32:35], v[166:169], v[192:195], v[32:35]
	v_mfma_f32_16x16x32_bf16 v[36:39], v[158:161], v[192:195], v[36:39]
	v_mfma_f32_16x16x32_bf16 v[20:23], v[158:161], v[214:217], v[20:23]
	v_mfma_f32_16x16x32_bf16 v[16:19], v[166:169], v[214:217], v[16:19]
	v_mfma_f32_16x16x32_bf16 v[0:3], v[166:169], v[222:225], v[0:3]
	v_mfma_f32_16x16x32_bf16 v[4:7], v[158:161], v[222:225], v[4:7]
	v_mfma_f32_16x16x32_bf16 v[52:55], v[162:165], v[178:181], v[52:55]
	v_mfma_f32_16x16x32_bf16 v[48:51], v[170:173], v[178:181], v[48:51]
	v_mfma_f32_16x16x32_bf16 v[32:35], v[170:173], v[196:199], v[32:35]
	v_mfma_f32_16x16x32_bf16 v[36:39], v[162:165], v[196:199], v[36:39]
	v_mfma_f32_16x16x32_bf16 v[20:23], v[162:165], v[218:221], v[20:23]
	v_mfma_f32_16x16x32_bf16 v[16:19], v[170:173], v[218:221], v[16:19]
	v_mfma_f32_16x16x32_bf16 v[0:3], v[170:173], v[226:229], v[0:3]
	v_mfma_f32_16x16x32_bf16 v[4:7], v[162:165], v[226:229], v[4:7]
	s_barrier
	s_add_i32 s51, s51, 2
	s_add_u32 s14, s14, 0x100
	s_addc_u32 s15, s15, 0
	s_add_u32 s49, s49, 0x100
	s_addc_u32 s50, s50, 0
	s_cmp_gt_u32 s51, 29
	s_cbranch_scc0 .LBB0_182
	s_and_b64 vcc, exec, s[62:63]
	s_cbranch_vccz .LBB0_185
	s_barrier

.LBB0_316:
	s_setprio 0
	s_waitcnt vmcnt(0)
	s_movk_i32 s64, 0xe7f0
	v_readlane_b32 s66, v255, 46
	v_readlane_b32 s51, v255, 47
	s_movk_i32 s67, 0x2000
	s_mov_b32 s71, 0x10000
	s_mov_b32 s77, 0x8000
	s_mov_b32 s53, 0x1b400000
	s_movk_i32 s54, 0x1000
	s_mov_b32 s65, -1
	s_barrier
